# thin kv tile: MFMA-computing waves run their stage compute first and issue their k+2 stage loads afterwards (idle waves load at stage start)
# speedup vs baseline: 1.0020x; 1.0001x over previous
; #define GLDS16(gp, lp) __builtin_amdgcn_global_load_lds((const unsigned*)(gp), (__attribute__((address_space(3))) unsigned*)(lp), 16, 0, 0)
; template <bool SWAP, class Epi, bool THIN = false> ...
;     ...
;     for (int st = 0; st < ns; ++st) {
;       asm volatile("s_waitcnt vmcnt(0)" ::: "memory");
;       __builtin_amdgcn_s_barrier();
;       asm volatile("" ::: "memory");
;       if (st + 1 < ns) {
;         char* nb = smem + ((st + 1) & 1) * 65536;
;         const int ko = (st + 1) * 64;
; #pragma unroll
;         for (int i = 0; i < 4; ++i) { GLDS16(A + (size_t)(ap[i] + ko), nb + tid * 16 + i * 8192); GLDS16(Bt + (size_t)(bp[i] + ko), nb + 32768 + tid * 16 + i * 8192); }
;       }
;       const char* sa = smem + (st & 1) * 65536 + (wr * 64 + fr) * 128;
;       const char* sb = smem + (st & 1) * 65536 + 32768 + (wc * 128 + fr) * 128;
;       if constexpr (THIN) {
;         if (wc == 0) {
; #pragma unroll
;           for (int ks = 0; ks < 2; ++ks) {
;             bf16x8 af[4], bf[2];
; #pragma unroll
;             for (int m = 0; m < 4; ++m) af[m] = *(const bf16x8*)(sa + m * 2048 + (((ks * 4 + fq) ^ swz) << 4));
; #pragma unroll
;             for (int n = 0; n < 2; ++n) bf[n] = *(const bf16x8*)(sb + n * 2048 + (((ks * 4 + fq) ^ swz) << 4));
; #pragma unroll
;             for (int m = 0; m < 4; ++m)
; #pragma unroll
;               for (int n = 0; n < 2; ++n)
;                 acc[m][n] = SWAP ? __builtin_amdgcn_mfma_f32_16x16x32_bf16(bf[n], af[m], acc[m][n], 0, 0, 0)
;                                  : __builtin_amdgcn_mfma_f32_16x16x32_bf16(af[m], bf[n], acc[m][n], 0, 0, 0);
;           }
;         }
.LBB0_1527:
	s_or_b64 exec, exec, s[6:7]
	s_waitcnt vmcnt(5)
	s_barrier
	s_and_saveexec_b64 s[6:7], s[4:5]
	s_cbranch_execz .Lthin_nc_1
	ds_read_b128 v[94:97], v87
	ds_read_b128 v[98:101], v87 offset:2048
	ds_read_b128 v[102:105], v86
	ds_read_b128 v[106:109], v86 offset:2048
	s_waitcnt lgkmcnt(0)
	v_mfma_f32_16x16x32_bf16 v[34:37], v[94:97], v[102:105], v[34:37]
	v_mfma_f32_16x16x32_bf16 v[30:33], v[98:101], v[102:105], v[30:33]
	v_mfma_f32_16x16x32_bf16 v[26:29], v[94:97], v[106:109], v[26:29]
	v_mfma_f32_16x16x32_bf16 v[22:25], v[98:101], v[106:109], v[22:25]
	ds_read_b128 v[102:105], v86 offset:4096
	ds_read_b128 v[106:109], v86 offset:6144
	s_waitcnt lgkmcnt(0)
	v_mfma_f32_16x16x32_bf16 v[18:21], v[94:97], v[102:105], v[18:21]
	v_mfma_f32_16x16x32_bf16 v[10:13], v[94:97], v[106:109], v[10:13]
	ds_read_b128 v[94:97], v89
	v_mfma_f32_16x16x32_bf16 v[14:17], v[98:101], v[102:105], v[14:17]
	v_mfma_f32_16x16x32_bf16 v[4:7], v[98:101], v[106:109], v[6:9]
	ds_read_b128 v[98:101], v89 offset:2048
	ds_read_b128 v[102:105], v88
	ds_read_b128 v[106:109], v88 offset:2048
	s_waitcnt lgkmcnt(0)
	v_mfma_f32_16x16x32_bf16 v[34:37], v[94:97], v[102:105], v[34:37]
	v_mfma_f32_16x16x32_bf16 v[30:33], v[98:101], v[102:105], v[30:33]
	v_mfma_f32_16x16x32_bf16 v[26:29], v[94:97], v[106:109], v[26:29]
	v_mfma_f32_16x16x32_bf16 v[22:25], v[98:101], v[106:109], v[22:25]
	ds_read_b128 v[102:105], v88 offset:4096
	ds_read_b128 v[106:109], v88 offset:6144
	s_waitcnt lgkmcnt(0)
	v_mfma_f32_16x16x32_bf16 v[18:21], v[94:97], v[102:105], v[18:21]
	v_mfma_f32_16x16x32_bf16 v[14:17], v[98:101], v[102:105], v[14:17]
	v_mfma_f32_16x16x32_bf16 v[10:13], v[94:97], v[106:109], v[10:13]
	v_mfma_f32_16x16x32_bf16 v[6:9], v[98:101], v[106:109], v[4:7]
	s_or_b64 exec, exec, s[6:7]
	v_readfirstlane_b32 s6, v56
	s_add_i32 m0, s6, 0x0
	v_lshl_add_u64 v[110:111], v[46:47], 0, s[26:27]
	global_load_lds_dwordx4 v[110:111], off
	v_or_b32_e32 v2, 0xc0, v38
	s_add_i32 m0, s6, 0x8000
	v_lshl_add_u64 v[110:111], v[2:3], 1, s[18:19]
	global_load_lds_dwordx4 v[110:111], off
	s_add_i32 m0, s6, 0x2000
	v_lshl_add_u64 v[110:111], v[48:49], 0, s[26:27]
	global_load_lds_dwordx4 v[110:111], off
	s_add_i32 m0, s6, 0x4000
	v_lshl_add_u64 v[110:111], v[50:51], 0, s[26:27]
	global_load_lds_dwordx4 v[110:111], off
	s_add_i32 m0, s6, 0x6000
	v_lshl_add_u64 v[110:111], v[52:53], 0, s[26:27]
	global_load_lds_dwordx4 v[110:111], off
	s_branch .LBB0_1529
.Lthin_nc_1:
	s_or_b64 exec, exec, s[6:7]
	v_readfirstlane_b32 s6, v56
	s_add_i32 m0, s6, 0x0
	v_lshl_add_u64 v[110:111], v[46:47], 0, s[26:27]
	global_load_lds_dwordx4 v[110:111], off
	v_or_b32_e32 v2, 0xc0, v38
	s_add_i32 m0, s6, 0x8000
	v_lshl_add_u64 v[110:111], v[2:3], 1, s[18:19]
	global_load_lds_dwordx4 v[110:111], off
	s_add_i32 m0, s6, 0x2000
	v_lshl_add_u64 v[110:111], v[48:49], 0, s[26:27]
	global_load_lds_dwordx4 v[110:111], off
	s_add_i32 m0, s6, 0x4000
	v_lshl_add_u64 v[110:111], v[50:51], 0, s[26:27]
	global_load_lds_dwordx4 v[110:111], off
	s_add_i32 m0, s6, 0x6000
	v_lshl_add_u64 v[110:111], v[52:53], 0, s[26:27]
	global_load_lds_dwordx4 v[110:111], off
.LBB0_1529:
	s_or_b64 exec, exec, s[6:7]
	s_waitcnt vmcnt(5)
	s_barrier
	s_and_saveexec_b64 s[6:7], s[4:5]
	s_cbranch_execz .Lthin_nc_2
	ds_read_b128 v[94:97], v119 offset:32768
	ds_read_b128 v[98:101], v119 offset:34816
	ds_read_b128 v[102:105], v118
	ds_read_b128 v[106:109], v118 offset:2048
	s_waitcnt lgkmcnt(0)
	v_mfma_f32_16x16x32_bf16 v[34:37], v[94:97], v[102:105], v[34:37]
	v_mfma_f32_16x16x32_bf16 v[30:33], v[98:101], v[102:105], v[30:33]
	v_mfma_f32_16x16x32_bf16 v[26:29], v[94:97], v[106:109], v[26:29]
	v_mfma_f32_16x16x32_bf16 v[22:25], v[98:101], v[106:109], v[22:25]
	ds_read_b128 v[102:105], v118 offset:4096
	ds_read_b128 v[106:109], v118 offset:6144
	s_waitcnt lgkmcnt(0)
	v_mfma_f32_16x16x32_bf16 v[18:21], v[94:97], v[102:105], v[18:21]
	v_mfma_f32_16x16x32_bf16 v[10:13], v[94:97], v[106:109], v[10:13]
	ds_read_b128 v[94:97], v121 offset:32768
	v_mfma_f32_16x16x32_bf16 v[14:17], v[98:101], v[102:105], v[14:17]
	v_mfma_f32_16x16x32_bf16 v[4:7], v[98:101], v[106:109], v[6:9]
	ds_read_b128 v[98:101], v121 offset:34816
	ds_read_b128 v[102:105], v120
	ds_read_b128 v[106:109], v120 offset:2048
	s_waitcnt lgkmcnt(0)
	v_mfma_f32_16x16x32_bf16 v[34:37], v[94:97], v[102:105], v[34:37]
	v_mfma_f32_16x16x32_bf16 v[30:33], v[98:101], v[102:105], v[30:33]
	v_mfma_f32_16x16x32_bf16 v[26:29], v[94:97], v[106:109], v[26:29]
	v_mfma_f32_16x16x32_bf16 v[22:25], v[98:101], v[106:109], v[22:25]
	ds_read_b128 v[102:105], v120 offset:4096
	ds_read_b128 v[106:109], v120 offset:6144
	s_waitcnt lgkmcnt(0)
	v_mfma_f32_16x16x32_bf16 v[18:21], v[94:97], v[102:105], v[18:21]
	v_mfma_f32_16x16x32_bf16 v[14:17], v[98:101], v[102:105], v[14:17]
	v_mfma_f32_16x16x32_bf16 v[10:13], v[94:97], v[106:109], v[10:13]
	v_mfma_f32_16x16x32_bf16 v[6:9], v[98:101], v[106:109], v[4:7]
	s_or_b64 exec, exec, s[6:7]
	v_readfirstlane_b32 s6, v56
	s_add_i32 m0, s6, 0x10000
	v_lshl_add_u64 v[110:111], v[46:47], 0, s[28:29]
	global_load_lds_dwordx4 v[110:111], off
	v_or_b32_e32 v2, 0x100, v38
	s_add_i32 m0, s6, 0x18000
	v_lshl_add_u64 v[110:111], v[2:3], 1, s[18:19]
	global_load_lds_dwordx4 v[110:111], off
	s_add_i32 m0, s6, 0x12000
	v_lshl_add_u64 v[110:111], v[48:49], 0, s[28:29]
	global_load_lds_dwordx4 v[110:111], off
	s_add_i32 m0, s6, 0x14000
	v_lshl_add_u64 v[110:111], v[50:51], 0, s[28:29]
	global_load_lds_dwordx4 v[110:111], off
	s_add_i32 m0, s6, 0x16000
	v_lshl_add_u64 v[110:111], v[52:53], 0, s[28:29]
	global_load_lds_dwordx4 v[110:111], off
	s_branch .LBB0_1531
; #define GLDS16(gp, lp) __builtin_amdgcn_global_load_lds((const unsigned*)(gp), (__attribute__((address_space(3))) unsigned*)(lp), 16, 0, 0)
; template <bool SWAP, class Epi, bool THIN = false> ...
;     ...
;     for (int st = 0; st < ns; ++st) {
;       asm volatile("s_waitcnt vmcnt(0)" ::: "memory");
;       __builtin_amdgcn_s_barrier();
;       asm volatile("" ::: "memory");
;       if (st + 1 < ns) {
;         char* nb = smem + ((st + 1) & 1) * 65536;
;         const int ko = (st + 1) * 64;
; #pragma unroll
;         for (int i = 0; i < 4; ++i) { GLDS16(A + (size_t)(ap[i] + ko), nb + tid * 16 + i * 8192); GLDS16(Bt + (size_t)(bp[i] + ko), nb + 32768 + tid * 16 + i * 8192); }
;       }
;       const char* sa = smem + (st & 1) * 65536 + (wr * 64 + fr) * 128;
;       const char* sb = smem + (st & 1) * 65536 + 32768 + (wc * 128 + fr) * 128;
;       if constexpr (THIN) {
;         if (wc == 0) {
; #pragma unroll
;           for (int ks = 0; ks < 2; ++ks) {
;             bf16x8 af[4], bf[2];
; #pragma unroll
;             for (int m = 0; m < 4; ++m) af[m] = *(const bf16x8*)(sa + m * 2048 + (((ks * 4 + fq) ^ swz) << 4));
; #pragma unroll
;             for (int n = 0; n < 2; ++n) bf[n] = *(const bf16x8*)(sb + n * 2048 + (((ks * 4 + fq) ^ swz) << 4));
; #pragma unroll
;             for (int m = 0; m < 4; ++m)
; #pragma unroll
;               for (int n = 0; n < 2; ++n)
;                 acc[m][n] = SWAP ? __builtin_amdgcn_mfma_f32_16x16x32_bf16(bf[n], af[m], acc[m][n], 0, 0, 0)
;                                  : __builtin_amdgcn_mfma_f32_16x16x32_bf16(af[m], bf[n], acc[m][n], 0, 0, 0);
;           }
;         }
.Lthin_nc_2:
	s_or_b64 exec, exec, s[6:7]
	v_readfirstlane_b32 s6, v56
	s_add_i32 m0, s6, 0x10000
	v_lshl_add_u64 v[110:111], v[46:47], 0, s[28:29]
	global_load_lds_dwordx4 v[110:111], off
	v_or_b32_e32 v2, 0x100, v38
	s_add_i32 m0, s6, 0x18000
	v_lshl_add_u64 v[110:111], v[2:3], 1, s[18:19]
	global_load_lds_dwordx4 v[110:111], off
	s_add_i32 m0, s6, 0x12000
	v_lshl_add_u64 v[110:111], v[48:49], 0, s[28:29]
	global_load_lds_dwordx4 v[110:111], off
	s_add_i32 m0, s6, 0x14000
	v_lshl_add_u64 v[110:111], v[50:51], 0, s[28:29]
	global_load_lds_dwordx4 v[110:111], off
	s_add_i32 m0, s6, 0x16000
	v_lshl_add_u64 v[110:111], v[52:53], 0, s[28:29]
	global_load_lds_dwordx4 v[110:111], off
.LBB0_1531:
	s_or_b64 exec, exec, s[6:7]
	s_waitcnt vmcnt(5)
	s_barrier
	s_and_saveexec_b64 s[6:7], s[4:5]
	s_cbranch_execz .Lthin_nc_3
	ds_read_b128 v[94:97], v83 offset:32768
	ds_read_b128 v[98:101], v83 offset:34816
	ds_read_b128 v[102:105], v82
	ds_read_b128 v[106:109], v82 offset:2048
	s_waitcnt lgkmcnt(0)
	v_mfma_f32_16x16x32_bf16 v[34:37], v[94:97], v[102:105], v[34:37]
	v_mfma_f32_16x16x32_bf16 v[30:33], v[98:101], v[102:105], v[30:33]
	v_mfma_f32_16x16x32_bf16 v[26:29], v[94:97], v[106:109], v[26:29]
	v_mfma_f32_16x16x32_bf16 v[22:25], v[98:101], v[106:109], v[22:25]
	ds_read_b128 v[102:105], v82 offset:4096
	ds_read_b128 v[106:109], v82 offset:6144
	s_waitcnt lgkmcnt(0)
	v_mfma_f32_16x16x32_bf16 v[18:21], v[94:97], v[102:105], v[18:21]
	v_mfma_f32_16x16x32_bf16 v[10:13], v[94:97], v[106:109], v[10:13]
	ds_read_b128 v[94:97], v85 offset:32768
	v_mfma_f32_16x16x32_bf16 v[14:17], v[98:101], v[102:105], v[14:17]
	v_mfma_f32_16x16x32_bf16 v[4:7], v[98:101], v[106:109], v[6:9]
	ds_read_b128 v[98:101], v85 offset:34816
	ds_read_b128 v[102:105], v84
	ds_read_b128 v[106:109], v84 offset:2048
	s_waitcnt lgkmcnt(0)
	v_mfma_f32_16x16x32_bf16 v[34:37], v[94:97], v[102:105], v[34:37]
	v_mfma_f32_16x16x32_bf16 v[30:33], v[98:101], v[102:105], v[30:33]
	v_mfma_f32_16x16x32_bf16 v[26:29], v[94:97], v[106:109], v[26:29]
	v_mfma_f32_16x16x32_bf16 v[22:25], v[98:101], v[106:109], v[22:25]
	ds_read_b128 v[102:105], v84 offset:4096
	ds_read_b128 v[106:109], v84 offset:6144
	s_waitcnt lgkmcnt(0)
	v_mfma_f32_16x16x32_bf16 v[18:21], v[94:97], v[102:105], v[18:21]
	v_mfma_f32_16x16x32_bf16 v[14:17], v[98:101], v[102:105], v[14:17]
	v_mfma_f32_16x16x32_bf16 v[10:13], v[94:97], v[106:109], v[10:13]
	v_mfma_f32_16x16x32_bf16 v[6:9], v[98:101], v[106:109], v[4:7]
	s_or_b64 exec, exec, s[6:7]
	v_readfirstlane_b32 s6, v56
	s_add_i32 m0, s6, 0x1a000
	v_lshl_add_u64 v[110:111], v[46:47], 0, s[38:39]
	global_load_lds_dwordx4 v[110:111], off
	v_or_b32_e32 v2, 0x140, v38
	s_add_i32 m0, s6, 0x22000
	v_lshl_add_u64 v[110:111], v[2:3], 1, s[18:19]
	global_load_lds_dwordx4 v[110:111], off
	s_add_i32 m0, s6, 0x1c000
	v_lshl_add_u64 v[110:111], v[48:49], 0, s[38:39]
	global_load_lds_dwordx4 v[110:111], off
	s_add_i32 m0, s6, 0x1e000
	v_lshl_add_u64 v[110:111], v[50:51], 0, s[38:39]
	global_load_lds_dwordx4 v[110:111], off
	s_add_i32 m0, s6, 0x20000
	v_lshl_add_u64 v[110:111], v[52:53], 0, s[38:39]
	global_load_lds_dwordx4 v[110:111], off
	s_branch .LBB0_1533
.Lthin_nc_3:
	s_or_b64 exec, exec, s[6:7]
	v_readfirstlane_b32 s6, v56
	s_add_i32 m0, s6, 0x1a000
	v_lshl_add_u64 v[110:111], v[46:47], 0, s[38:39]
	global_load_lds_dwordx4 v[110:111], off
	v_or_b32_e32 v2, 0x140, v38
	s_add_i32 m0, s6, 0x22000
	v_lshl_add_u64 v[110:111], v[2:3], 1, s[18:19]
	global_load_lds_dwordx4 v[110:111], off
	s_add_i32 m0, s6, 0x1c000
	v_lshl_add_u64 v[110:111], v[48:49], 0, s[38:39]
	global_load_lds_dwordx4 v[110:111], off
	s_add_i32 m0, s6, 0x1e000
	v_lshl_add_u64 v[110:111], v[50:51], 0, s[38:39]
	global_load_lds_dwordx4 v[110:111], off
	s_add_i32 m0, s6, 0x20000
	v_lshl_add_u64 v[110:111], v[52:53], 0, s[38:39]
	global_load_lds_dwordx4 v[110:111], off
.LBB0_1533:
	s_or_b64 exec, exec, s[6:7]
	s_waitcnt vmcnt(5)
	s_barrier
	s_and_saveexec_b64 s[6:7], s[4:5]
	s_cbranch_execz .Lthin_nc_4
	ds_read_b128 v[94:97], v87
	ds_read_b128 v[98:101], v87 offset:2048
	ds_read_b128 v[102:105], v86
	ds_read_b128 v[106:109], v86 offset:2048
	s_waitcnt lgkmcnt(0)
	v_mfma_f32_16x16x32_bf16 v[34:37], v[94:97], v[102:105], v[34:37]
	v_mfma_f32_16x16x32_bf16 v[30:33], v[98:101], v[102:105], v[30:33]
	v_mfma_f32_16x16x32_bf16 v[26:29], v[94:97], v[106:109], v[26:29]
	v_mfma_f32_16x16x32_bf16 v[22:25], v[98:101], v[106:109], v[22:25]
	ds_read_b128 v[102:105], v86 offset:4096
	ds_read_b128 v[106:109], v86 offset:6144
	s_waitcnt lgkmcnt(0)
	v_mfma_f32_16x16x32_bf16 v[18:21], v[94:97], v[102:105], v[18:21]
	v_mfma_f32_16x16x32_bf16 v[10:13], v[94:97], v[106:109], v[10:13]
	ds_read_b128 v[94:97], v89
	v_mfma_f32_16x16x32_bf16 v[14:17], v[98:101], v[102:105], v[14:17]
	v_mfma_f32_16x16x32_bf16 v[4:7], v[98:101], v[106:109], v[6:9]
	ds_read_b128 v[98:101], v89 offset:2048
	ds_read_b128 v[102:105], v88
	ds_read_b128 v[106:109], v88 offset:2048
	s_waitcnt lgkmcnt(0)
	v_mfma_f32_16x16x32_bf16 v[34:37], v[94:97], v[102:105], v[34:37]
	v_mfma_f32_16x16x32_bf16 v[30:33], v[98:101], v[102:105], v[30:33]
	v_mfma_f32_16x16x32_bf16 v[26:29], v[94:97], v[106:109], v[26:29]
	v_mfma_f32_16x16x32_bf16 v[22:25], v[98:101], v[106:109], v[22:25]
	ds_read_b128 v[102:105], v88 offset:4096
	ds_read_b128 v[106:109], v88 offset:6144
	s_waitcnt lgkmcnt(0)
	v_mfma_f32_16x16x32_bf16 v[18:21], v[94:97], v[102:105], v[18:21]
	v_mfma_f32_16x16x32_bf16 v[14:17], v[98:101], v[102:105], v[14:17]
	v_mfma_f32_16x16x32_bf16 v[10:13], v[94:97], v[106:109], v[10:13]
	v_mfma_f32_16x16x32_bf16 v[6:9], v[98:101], v[106:109], v[4:7]
	s_or_b64 exec, exec, s[6:7]
	v_readfirstlane_b32 s6, v56
	s_add_i32 m0, s6, 0x0
	v_lshl_add_u64 v[110:111], v[46:47], 0, s[40:41]
	global_load_lds_dwordx4 v[110:111], off
	v_or_b32_e32 v2, 0x180, v38
	s_add_i32 m0, s6, 0x8000
	v_lshl_add_u64 v[110:111], v[2:3], 1, s[18:19]
	global_load_lds_dwordx4 v[110:111], off
	s_add_i32 m0, s6, 0x2000
	v_lshl_add_u64 v[110:111], v[48:49], 0, s[40:41]
	global_load_lds_dwordx4 v[110:111], off
	s_add_i32 m0, s6, 0x4000
	v_lshl_add_u64 v[110:111], v[50:51], 0, s[40:41]
	global_load_lds_dwordx4 v[110:111], off
	s_add_i32 m0, s6, 0x6000
	v_lshl_add_u64 v[110:111], v[52:53], 0, s[40:41]
	global_load_lds_dwordx4 v[110:111], off
	s_branch .LBB0_1535
; #define GLDS16(gp, lp) __builtin_amdgcn_global_load_lds((const unsigned*)(gp), (__attribute__((address_space(3))) unsigned*)(lp), 16, 0, 0)
; template <bool SWAP, class Epi, bool THIN = false> ...
;     ...
;     for (int st = 0; st < ns; ++st) {
;       asm volatile("s_waitcnt vmcnt(0)" ::: "memory");
;       __builtin_amdgcn_s_barrier();
;       asm volatile("" ::: "memory");
;       if (st + 1 < ns) {
;         char* nb = smem + ((st + 1) & 1) * 65536;
;         const int ko = (st + 1) * 64;
; #pragma unroll
;         for (int i = 0; i < 4; ++i) { GLDS16(A + (size_t)(ap[i] + ko), nb + tid * 16 + i * 8192); GLDS16(Bt + (size_t)(bp[i] + ko), nb + 32768 + tid * 16 + i * 8192); }
;       }
;       const char* sa = smem + (st & 1) * 65536 + (wr * 64 + fr) * 128;
;       const char* sb = smem + (st & 1) * 65536 + 32768 + (wc * 128 + fr) * 128;
;       if constexpr (THIN) {
;         if (wc == 0) {
; #pragma unroll
;           for (int ks = 0; ks < 2; ++ks) {
;             bf16x8 af[4], bf[2];
; #pragma unroll
;             for (int m = 0; m < 4; ++m) af[m] = *(const bf16x8*)(sa + m * 2048 + (((ks * 4 + fq) ^ swz) << 4));
; #pragma unroll
;             for (int n = 0; n < 2; ++n) bf[n] = *(const bf16x8*)(sb + n * 2048 + (((ks * 4 + fq) ^ swz) << 4));
; #pragma unroll
;             for (int m = 0; m < 4; ++m)
; #pragma unroll
;               for (int n = 0; n < 2; ++n)
;                 acc[m][n] = SWAP ? __builtin_amdgcn_mfma_f32_16x16x32_bf16(bf[n], af[m], acc[m][n], 0, 0, 0)
;                                  : __builtin_amdgcn_mfma_f32_16x16x32_bf16(af[m], bf[n], acc[m][n], 0, 0, 0);
;           }
;         }
.Lthin_nc_4:
	s_or_b64 exec, exec, s[6:7]
	v_readfirstlane_b32 s6, v56
	s_add_i32 m0, s6, 0x0
	v_lshl_add_u64 v[110:111], v[46:47], 0, s[40:41]
	global_load_lds_dwordx4 v[110:111], off
	v_or_b32_e32 v2, 0x180, v38
	s_add_i32 m0, s6, 0x8000
	v_lshl_add_u64 v[110:111], v[2:3], 1, s[18:19]
	global_load_lds_dwordx4 v[110:111], off
	s_add_i32 m0, s6, 0x2000
	v_lshl_add_u64 v[110:111], v[48:49], 0, s[40:41]
	global_load_lds_dwordx4 v[110:111], off
	s_add_i32 m0, s6, 0x4000
	v_lshl_add_u64 v[110:111], v[50:51], 0, s[40:41]
	global_load_lds_dwordx4 v[110:111], off
	s_add_i32 m0, s6, 0x6000
	v_lshl_add_u64 v[110:111], v[52:53], 0, s[40:41]
	global_load_lds_dwordx4 v[110:111], off
.LBB0_1535:
	s_or_b64 exec, exec, s[6:7]
	s_waitcnt vmcnt(5)
	s_barrier
	s_and_saveexec_b64 s[6:7], s[4:5]
	s_cbranch_execz .Lthin_nc_5
	ds_read_b128 v[94:97], v119 offset:32768
	ds_read_b128 v[98:101], v119 offset:34816
	ds_read_b128 v[102:105], v118
	ds_read_b128 v[106:109], v118 offset:2048
	s_waitcnt lgkmcnt(0)
	v_mfma_f32_16x16x32_bf16 v[34:37], v[94:97], v[102:105], v[34:37]
	v_mfma_f32_16x16x32_bf16 v[30:33], v[98:101], v[102:105], v[30:33]
	v_mfma_f32_16x16x32_bf16 v[26:29], v[94:97], v[106:109], v[26:29]
	v_mfma_f32_16x16x32_bf16 v[22:25], v[98:101], v[106:109], v[22:25]
	ds_read_b128 v[102:105], v118 offset:4096
	ds_read_b128 v[106:109], v118 offset:6144
	s_waitcnt lgkmcnt(0)
	v_mfma_f32_16x16x32_bf16 v[18:21], v[94:97], v[102:105], v[18:21]
	v_mfma_f32_16x16x32_bf16 v[10:13], v[94:97], v[106:109], v[10:13]
	ds_read_b128 v[94:97], v121 offset:32768
	v_mfma_f32_16x16x32_bf16 v[14:17], v[98:101], v[102:105], v[14:17]
	v_mfma_f32_16x16x32_bf16 v[4:7], v[98:101], v[106:109], v[6:9]
	ds_read_b128 v[98:101], v121 offset:34816
	ds_read_b128 v[102:105], v120
	ds_read_b128 v[106:109], v120 offset:2048
	s_waitcnt lgkmcnt(0)
	v_mfma_f32_16x16x32_bf16 v[34:37], v[94:97], v[102:105], v[34:37]
	v_mfma_f32_16x16x32_bf16 v[30:33], v[98:101], v[102:105], v[30:33]
	v_mfma_f32_16x16x32_bf16 v[26:29], v[94:97], v[106:109], v[26:29]
	v_mfma_f32_16x16x32_bf16 v[22:25], v[98:101], v[106:109], v[22:25]
	ds_read_b128 v[102:105], v120 offset:4096
	ds_read_b128 v[106:109], v120 offset:6144
	s_waitcnt lgkmcnt(0)
	v_mfma_f32_16x16x32_bf16 v[18:21], v[94:97], v[102:105], v[18:21]
	v_mfma_f32_16x16x32_bf16 v[14:17], v[98:101], v[102:105], v[14:17]
	v_mfma_f32_16x16x32_bf16 v[10:13], v[94:97], v[106:109], v[10:13]
	v_mfma_f32_16x16x32_bf16 v[6:9], v[98:101], v[106:109], v[4:7]
	s_or_b64 exec, exec, s[6:7]
	v_readfirstlane_b32 s6, v56
	s_add_i32 m0, s6, 0x10000
	v_lshl_add_u64 v[110:111], v[46:47], 0, s[42:43]
	global_load_lds_dwordx4 v[110:111], off
	v_or_b32_e32 v2, 0x1c0, v38
	s_add_i32 m0, s6, 0x18000
	v_lshl_add_u64 v[110:111], v[2:3], 1, s[18:19]
	global_load_lds_dwordx4 v[110:111], off
	s_add_i32 m0, s6, 0x12000
	v_lshl_add_u64 v[110:111], v[48:49], 0, s[42:43]
	global_load_lds_dwordx4 v[110:111], off
	s_add_i32 m0, s6, 0x14000
	v_lshl_add_u64 v[110:111], v[50:51], 0, s[42:43]
	global_load_lds_dwordx4 v[110:111], off
	s_add_i32 m0, s6, 0x16000
	v_lshl_add_u64 v[110:111], v[52:53], 0, s[42:43]
	global_load_lds_dwordx4 v[110:111], off
	s_branch .LBB0_1537
.Lthin_nc_5:
	s_or_b64 exec, exec, s[6:7]
	v_readfirstlane_b32 s6, v56
	s_add_i32 m0, s6, 0x10000
	v_lshl_add_u64 v[110:111], v[46:47], 0, s[42:43]
	global_load_lds_dwordx4 v[110:111], off
	v_or_b32_e32 v2, 0x1c0, v38
	s_add_i32 m0, s6, 0x18000
	v_lshl_add_u64 v[110:111], v[2:3], 1, s[18:19]
	global_load_lds_dwordx4 v[110:111], off
	s_add_i32 m0, s6, 0x12000
	v_lshl_add_u64 v[110:111], v[48:49], 0, s[42:43]
	global_load_lds_dwordx4 v[110:111], off
	s_add_i32 m0, s6, 0x14000
	v_lshl_add_u64 v[110:111], v[50:51], 0, s[42:43]
	global_load_lds_dwordx4 v[110:111], off
	s_add_i32 m0, s6, 0x16000
	v_lshl_add_u64 v[110:111], v[52:53], 0, s[42:43]
	global_load_lds_dwordx4 v[110:111], off
.LBB0_1537:
	s_or_b64 exec, exec, s[6:7]
	s_waitcnt vmcnt(5)
	s_barrier
	s_and_saveexec_b64 s[6:7], s[4:5]
	s_cbranch_execz .Lthin_nc_6
	ds_read_b128 v[94:97], v83 offset:32768
	ds_read_b128 v[98:101], v83 offset:34816
	ds_read_b128 v[102:105], v82
	ds_read_b128 v[106:109], v82 offset:2048
	s_waitcnt lgkmcnt(0)
	v_mfma_f32_16x16x32_bf16 v[34:37], v[94:97], v[102:105], v[34:37]
	v_mfma_f32_16x16x32_bf16 v[30:33], v[98:101], v[102:105], v[30:33]
	v_mfma_f32_16x16x32_bf16 v[26:29], v[94:97], v[106:109], v[26:29]
	v_mfma_f32_16x16x32_bf16 v[22:25], v[98:101], v[106:109], v[22:25]
	ds_read_b128 v[102:105], v82 offset:4096
	ds_read_b128 v[106:109], v82 offset:6144
	s_waitcnt lgkmcnt(0)
	v_mfma_f32_16x16x32_bf16 v[18:21], v[94:97], v[102:105], v[18:21]
	v_mfma_f32_16x16x32_bf16 v[10:13], v[94:97], v[106:109], v[10:13]
	ds_read_b128 v[94:97], v85 offset:32768
	v_mfma_f32_16x16x32_bf16 v[14:17], v[98:101], v[102:105], v[14:17]
	v_mfma_f32_16x16x32_bf16 v[4:7], v[98:101], v[106:109], v[6:9]
	ds_read_b128 v[98:101], v85 offset:34816
	ds_read_b128 v[102:105], v84
	ds_read_b128 v[106:109], v84 offset:2048
	s_waitcnt lgkmcnt(0)
	v_mfma_f32_16x16x32_bf16 v[34:37], v[94:97], v[102:105], v[34:37]
	v_mfma_f32_16x16x32_bf16 v[30:33], v[98:101], v[102:105], v[30:33]
	v_mfma_f32_16x16x32_bf16 v[26:29], v[94:97], v[106:109], v[26:29]
	v_mfma_f32_16x16x32_bf16 v[22:25], v[98:101], v[106:109], v[22:25]
	ds_read_b128 v[102:105], v84 offset:4096
	ds_read_b128 v[106:109], v84 offset:6144
	s_waitcnt lgkmcnt(0)
	v_mfma_f32_16x16x32_bf16 v[18:21], v[94:97], v[102:105], v[18:21]
	v_mfma_f32_16x16x32_bf16 v[14:17], v[98:101], v[102:105], v[14:17]
	v_mfma_f32_16x16x32_bf16 v[10:13], v[94:97], v[106:109], v[10:13]
	v_mfma_f32_16x16x32_bf16 v[6:9], v[98:101], v[106:109], v[4:7]
	s_or_b64 exec, exec, s[6:7]
	v_readfirstlane_b32 s6, v56
	s_add_i32 m0, s6, 0x1a000
	v_lshl_add_u64 v[110:111], v[46:47], 0, s[44:45]
	global_load_lds_dwordx4 v[110:111], off
	v_or_b32_e32 v2, 0x200, v38
	s_add_i32 m0, s6, 0x22000
	v_lshl_add_u64 v[110:111], v[2:3], 1, s[18:19]
	global_load_lds_dwordx4 v[110:111], off
	s_add_i32 m0, s6, 0x1c000
	v_lshl_add_u64 v[110:111], v[48:49], 0, s[44:45]
	global_load_lds_dwordx4 v[110:111], off
	s_add_i32 m0, s6, 0x1e000
	v_lshl_add_u64 v[110:111], v[50:51], 0, s[44:45]
	global_load_lds_dwordx4 v[110:111], off
	s_add_i32 m0, s6, 0x20000
	v_lshl_add_u64 v[110:111], v[52:53], 0, s[44:45]
	global_load_lds_dwordx4 v[110:111], off
	s_branch .LBB0_1539
; #define GLDS16(gp, lp) __builtin_amdgcn_global_load_lds((const unsigned*)(gp), (__attribute__((address_space(3))) unsigned*)(lp), 16, 0, 0)
; template <bool SWAP, class Epi, bool THIN = false> ...
;     ...
;     for (int st = 0; st < ns; ++st) {
;       asm volatile("s_waitcnt vmcnt(0)" ::: "memory");
;       __builtin_amdgcn_s_barrier();
;       asm volatile("" ::: "memory");
;       if (st + 1 < ns) {
;         char* nb = smem + ((st + 1) & 1) * 65536;
;         const int ko = (st + 1) * 64;
; #pragma unroll
;         for (int i = 0; i < 4; ++i) { GLDS16(A + (size_t)(ap[i] + ko), nb + tid * 16 + i * 8192); GLDS16(Bt + (size_t)(bp[i] + ko), nb + 32768 + tid * 16 + i * 8192); }
;       }
;       const char* sa = smem + (st & 1) * 65536 + (wr * 64 + fr) * 128;
;       const char* sb = smem + (st & 1) * 65536 + 32768 + (wc * 128 + fr) * 128;
;       if constexpr (THIN) {
;         if (wc == 0) {
; #pragma unroll
;           for (int ks = 0; ks < 2; ++ks) {
;             bf16x8 af[4], bf[2];
; #pragma unroll
;             for (int m = 0; m < 4; ++m) af[m] = *(const bf16x8*)(sa + m * 2048 + (((ks * 4 + fq) ^ swz) << 4));
; #pragma unroll
;             for (int n = 0; n < 2; ++n) bf[n] = *(const bf16x8*)(sb + n * 2048 + (((ks * 4 + fq) ^ swz) << 4));
; #pragma unroll
;             for (int m = 0; m < 4; ++m)
; #pragma unroll
;               for (int n = 0; n < 2; ++n)
;                 acc[m][n] = SWAP ? __builtin_amdgcn_mfma_f32_16x16x32_bf16(bf[n], af[m], acc[m][n], 0, 0, 0)
;                                  : __builtin_amdgcn_mfma_f32_16x16x32_bf16(af[m], bf[n], acc[m][n], 0, 0, 0);
;           }
;         }
.Lthin_nc_6:
	s_or_b64 exec, exec, s[6:7]
	v_readfirstlane_b32 s6, v56
	s_add_i32 m0, s6, 0x1a000
	v_lshl_add_u64 v[110:111], v[46:47], 0, s[44:45]
	global_load_lds_dwordx4 v[110:111], off
	v_or_b32_e32 v2, 0x200, v38
	s_add_i32 m0, s6, 0x22000
	v_lshl_add_u64 v[110:111], v[2:3], 1, s[18:19]
	global_load_lds_dwordx4 v[110:111], off
	s_add_i32 m0, s6, 0x1c000
	v_lshl_add_u64 v[110:111], v[48:49], 0, s[44:45]
	global_load_lds_dwordx4 v[110:111], off
	s_add_i32 m0, s6, 0x1e000
	v_lshl_add_u64 v[110:111], v[50:51], 0, s[44:45]
	global_load_lds_dwordx4 v[110:111], off
	s_add_i32 m0, s6, 0x20000
	v_lshl_add_u64 v[110:111], v[52:53], 0, s[44:45]
	global_load_lds_dwordx4 v[110:111], off
.LBB0_1539:
	s_or_b64 exec, exec, s[6:7]
	s_waitcnt vmcnt(5)
	s_barrier
	s_and_saveexec_b64 s[6:7], s[4:5]
	s_cbranch_execz .Lthin_nc_7
	ds_read_b128 v[94:97], v87
	ds_read_b128 v[98:101], v87 offset:2048
	ds_read_b128 v[102:105], v86
	ds_read_b128 v[106:109], v86 offset:2048
	s_waitcnt lgkmcnt(0)
	v_mfma_f32_16x16x32_bf16 v[34:37], v[94:97], v[102:105], v[34:37]
	v_mfma_f32_16x16x32_bf16 v[30:33], v[98:101], v[102:105], v[30:33]
	v_mfma_f32_16x16x32_bf16 v[26:29], v[94:97], v[106:109], v[26:29]
	v_mfma_f32_16x16x32_bf16 v[22:25], v[98:101], v[106:109], v[22:25]
	ds_read_b128 v[102:105], v86 offset:4096
	ds_read_b128 v[106:109], v86 offset:6144
	s_waitcnt lgkmcnt(0)
	v_mfma_f32_16x16x32_bf16 v[18:21], v[94:97], v[102:105], v[18:21]
	v_mfma_f32_16x16x32_bf16 v[10:13], v[94:97], v[106:109], v[10:13]
	ds_read_b128 v[94:97], v89
	v_mfma_f32_16x16x32_bf16 v[14:17], v[98:101], v[102:105], v[14:17]
	v_mfma_f32_16x16x32_bf16 v[4:7], v[98:101], v[106:109], v[6:9]
	ds_read_b128 v[98:101], v89 offset:2048
	ds_read_b128 v[102:105], v88
	ds_read_b128 v[106:109], v88 offset:2048
	s_waitcnt lgkmcnt(0)
	v_mfma_f32_16x16x32_bf16 v[34:37], v[94:97], v[102:105], v[34:37]
	v_mfma_f32_16x16x32_bf16 v[30:33], v[98:101], v[102:105], v[30:33]
	v_mfma_f32_16x16x32_bf16 v[26:29], v[94:97], v[106:109], v[26:29]
	v_mfma_f32_16x16x32_bf16 v[22:25], v[98:101], v[106:109], v[22:25]
	ds_read_b128 v[102:105], v88 offset:4096
	ds_read_b128 v[106:109], v88 offset:6144
	s_waitcnt lgkmcnt(0)
	v_mfma_f32_16x16x32_bf16 v[18:21], v[94:97], v[102:105], v[18:21]
	v_mfma_f32_16x16x32_bf16 v[14:17], v[98:101], v[102:105], v[14:17]
	v_mfma_f32_16x16x32_bf16 v[10:13], v[94:97], v[106:109], v[10:13]
	v_mfma_f32_16x16x32_bf16 v[6:9], v[98:101], v[106:109], v[4:7]
	s_or_b64 exec, exec, s[6:7]
	v_readfirstlane_b32 s6, v56
	s_add_i32 m0, s6, 0x0
	v_lshl_add_u64 v[110:111], v[46:47], 0, s[48:49]
	global_load_lds_dwordx4 v[110:111], off
	v_or_b32_e32 v2, 0x240, v38
	s_add_i32 m0, s6, 0x8000
	v_lshl_add_u64 v[110:111], v[2:3], 1, s[18:19]
	global_load_lds_dwordx4 v[110:111], off
	s_add_i32 m0, s6, 0x2000
	v_lshl_add_u64 v[110:111], v[48:49], 0, s[48:49]
	global_load_lds_dwordx4 v[110:111], off
	s_add_i32 m0, s6, 0x4000
	v_lshl_add_u64 v[110:111], v[50:51], 0, s[48:49]
	global_load_lds_dwordx4 v[110:111], off
	s_add_i32 m0, s6, 0x6000
	v_lshl_add_u64 v[110:111], v[52:53], 0, s[48:49]
	global_load_lds_dwordx4 v[110:111], off
	s_branch .LBB0_1541
.Lthin_nc_7:
	s_or_b64 exec, exec, s[6:7]
	v_readfirstlane_b32 s6, v56
	s_add_i32 m0, s6, 0x0
	v_lshl_add_u64 v[110:111], v[46:47], 0, s[48:49]
	global_load_lds_dwordx4 v[110:111], off
	v_or_b32_e32 v2, 0x240, v38
	s_add_i32 m0, s6, 0x8000
	v_lshl_add_u64 v[110:111], v[2:3], 1, s[18:19]
	global_load_lds_dwordx4 v[110:111], off
	s_add_i32 m0, s6, 0x2000
	v_lshl_add_u64 v[110:111], v[48:49], 0, s[48:49]
	global_load_lds_dwordx4 v[110:111], off
	s_add_i32 m0, s6, 0x4000
	v_lshl_add_u64 v[110:111], v[50:51], 0, s[48:49]
	global_load_lds_dwordx4 v[110:111], off
	s_add_i32 m0, s6, 0x6000
	v_lshl_add_u64 v[110:111], v[52:53], 0, s[48:49]
	global_load_lds_dwordx4 v[110:111], off
.LBB0_1541:
	s_or_b64 exec, exec, s[6:7]
	s_waitcnt vmcnt(5)
	s_barrier
	s_and_saveexec_b64 s[6:7], s[4:5]
	s_cbranch_execz .Lthin_nc_8
	ds_read_b128 v[94:97], v119 offset:32768
	ds_read_b128 v[98:101], v119 offset:34816
	ds_read_b128 v[102:105], v118
	ds_read_b128 v[106:109], v118 offset:2048
	s_waitcnt lgkmcnt(0)
	v_mfma_f32_16x16x32_bf16 v[34:37], v[94:97], v[102:105], v[34:37]
	v_mfma_f32_16x16x32_bf16 v[30:33], v[98:101], v[102:105], v[30:33]
	v_mfma_f32_16x16x32_bf16 v[26:29], v[94:97], v[106:109], v[26:29]
	v_mfma_f32_16x16x32_bf16 v[22:25], v[98:101], v[106:109], v[22:25]
	ds_read_b128 v[102:105], v118 offset:4096
	ds_read_b128 v[106:109], v118 offset:6144
	s_waitcnt lgkmcnt(0)
	v_mfma_f32_16x16x32_bf16 v[18:21], v[94:97], v[102:105], v[18:21]
	v_mfma_f32_16x16x32_bf16 v[10:13], v[94:97], v[106:109], v[10:13]
	ds_read_b128 v[94:97], v121 offset:32768
	v_mfma_f32_16x16x32_bf16 v[14:17], v[98:101], v[102:105], v[14:17]
	v_mfma_f32_16x16x32_bf16 v[4:7], v[98:101], v[106:109], v[6:9]
	ds_read_b128 v[98:101], v121 offset:34816
	ds_read_b128 v[102:105], v120
	ds_read_b128 v[106:109], v120 offset:2048
	s_waitcnt lgkmcnt(0)
	v_mfma_f32_16x16x32_bf16 v[34:37], v[94:97], v[102:105], v[34:37]
	v_mfma_f32_16x16x32_bf16 v[30:33], v[98:101], v[102:105], v[30:33]
	v_mfma_f32_16x16x32_bf16 v[26:29], v[94:97], v[106:109], v[26:29]
	v_mfma_f32_16x16x32_bf16 v[22:25], v[98:101], v[106:109], v[22:25]
	ds_read_b128 v[102:105], v120 offset:4096
	ds_read_b128 v[106:109], v120 offset:6144
	s_waitcnt lgkmcnt(0)
	v_mfma_f32_16x16x32_bf16 v[18:21], v[94:97], v[102:105], v[18:21]
	v_mfma_f32_16x16x32_bf16 v[14:17], v[98:101], v[102:105], v[14:17]
	v_mfma_f32_16x16x32_bf16 v[10:13], v[94:97], v[106:109], v[10:13]
	v_mfma_f32_16x16x32_bf16 v[6:9], v[98:101], v[106:109], v[4:7]
	s_or_b64 exec, exec, s[6:7]
	v_readfirstlane_b32 s6, v56
	s_add_i32 m0, s6, 0x10000
	v_lshl_add_u64 v[110:111], v[46:47], 0, s[50:51]
	global_load_lds_dwordx4 v[110:111], off
	v_or_b32_e32 v2, 0x280, v38
	s_add_i32 m0, s6, 0x18000
	v_lshl_add_u64 v[110:111], v[2:3], 1, s[18:19]
	global_load_lds_dwordx4 v[110:111], off
	s_add_i32 m0, s6, 0x12000
	v_lshl_add_u64 v[110:111], v[48:49], 0, s[50:51]
	global_load_lds_dwordx4 v[110:111], off
	s_add_i32 m0, s6, 0x14000
	v_lshl_add_u64 v[110:111], v[50:51], 0, s[50:51]
	global_load_lds_dwordx4 v[110:111], off
	s_add_i32 m0, s6, 0x16000
	v_lshl_add_u64 v[110:111], v[52:53], 0, s[50:51]
	global_load_lds_dwordx4 v[110:111], off
	s_branch .LBB0_1543
; #define GLDS16(gp, lp) __builtin_amdgcn_global_load_lds((const unsigned*)(gp), (__attribute__((address_space(3))) unsigned*)(lp), 16, 0, 0)
; template <bool SWAP, class Epi, bool THIN = false> ...
;     ...
;     for (int st = 0; st < ns; ++st) {
;       asm volatile("s_waitcnt vmcnt(0)" ::: "memory");
;       __builtin_amdgcn_s_barrier();
;       asm volatile("" ::: "memory");
;       if (st + 1 < ns) {
;         char* nb = smem + ((st + 1) & 1) * 65536;
;         const int ko = (st + 1) * 64;
; #pragma unroll
;         for (int i = 0; i < 4; ++i) { GLDS16(A + (size_t)(ap[i] + ko), nb + tid * 16 + i * 8192); GLDS16(Bt + (size_t)(bp[i] + ko), nb + 32768 + tid * 16 + i * 8192); }
;       }
;       const char* sa = smem + (st & 1) * 65536 + (wr * 64 + fr) * 128;
;       const char* sb = smem + (st & 1) * 65536 + 32768 + (wc * 128 + fr) * 128;
;       if constexpr (THIN) {
;         if (wc == 0) {
; #pragma unroll
;           for (int ks = 0; ks < 2; ++ks) {
;             bf16x8 af[4], bf[2];
; #pragma unroll
;             for (int m = 0; m < 4; ++m) af[m] = *(const bf16x8*)(sa + m * 2048 + (((ks * 4 + fq) ^ swz) << 4));
; #pragma unroll
;             for (int n = 0; n < 2; ++n) bf[n] = *(const bf16x8*)(sb + n * 2048 + (((ks * 4 + fq) ^ swz) << 4));
; #pragma unroll
;             for (int m = 0; m < 4; ++m)
; #pragma unroll
;               for (int n = 0; n < 2; ++n)
;                 acc[m][n] = SWAP ? __builtin_amdgcn_mfma_f32_16x16x32_bf16(bf[n], af[m], acc[m][n], 0, 0, 0)
;                                  : __builtin_amdgcn_mfma_f32_16x16x32_bf16(af[m], bf[n], acc[m][n], 0, 0, 0);
;           }
;         }
.Lthin_nc_8:
	s_or_b64 exec, exec, s[6:7]
	v_readfirstlane_b32 s6, v56
	s_add_i32 m0, s6, 0x10000
	v_lshl_add_u64 v[110:111], v[46:47], 0, s[50:51]
	global_load_lds_dwordx4 v[110:111], off
	v_or_b32_e32 v2, 0x280, v38
	s_add_i32 m0, s6, 0x18000
	v_lshl_add_u64 v[110:111], v[2:3], 1, s[18:19]
	global_load_lds_dwordx4 v[110:111], off
	s_add_i32 m0, s6, 0x12000
	v_lshl_add_u64 v[110:111], v[48:49], 0, s[50:51]
	global_load_lds_dwordx4 v[110:111], off
	s_add_i32 m0, s6, 0x14000
	v_lshl_add_u64 v[110:111], v[50:51], 0, s[50:51]
	global_load_lds_dwordx4 v[110:111], off
	s_add_i32 m0, s6, 0x16000
	v_lshl_add_u64 v[110:111], v[52:53], 0, s[50:51]
	global_load_lds_dwordx4 v[110:111], off
.LBB0_1543:
	s_or_b64 exec, exec, s[6:7]
	s_waitcnt vmcnt(5)
	s_barrier
	s_and_saveexec_b64 s[6:7], s[4:5]
	s_cbranch_execz .Lthin_nc_9
	ds_read_b128 v[94:97], v83 offset:32768
	ds_read_b128 v[98:101], v83 offset:34816
	ds_read_b128 v[102:105], v82
	ds_read_b128 v[106:109], v82 offset:2048
	s_waitcnt lgkmcnt(0)
	v_mfma_f32_16x16x32_bf16 v[34:37], v[94:97], v[102:105], v[34:37]
	v_mfma_f32_16x16x32_bf16 v[30:33], v[98:101], v[102:105], v[30:33]
	v_mfma_f32_16x16x32_bf16 v[26:29], v[94:97], v[106:109], v[26:29]
	v_mfma_f32_16x16x32_bf16 v[22:25], v[98:101], v[106:109], v[22:25]
	ds_read_b128 v[102:105], v82 offset:4096
	ds_read_b128 v[106:109], v82 offset:6144
	s_waitcnt lgkmcnt(0)
	v_mfma_f32_16x16x32_bf16 v[18:21], v[94:97], v[102:105], v[18:21]
	v_mfma_f32_16x16x32_bf16 v[10:13], v[94:97], v[106:109], v[10:13]
	ds_read_b128 v[94:97], v85 offset:32768
	v_mfma_f32_16x16x32_bf16 v[14:17], v[98:101], v[102:105], v[14:17]
	v_mfma_f32_16x16x32_bf16 v[4:7], v[98:101], v[106:109], v[6:9]
	ds_read_b128 v[98:101], v85 offset:34816
	ds_read_b128 v[102:105], v84
	ds_read_b128 v[106:109], v84 offset:2048
	s_waitcnt lgkmcnt(0)
	v_mfma_f32_16x16x32_bf16 v[34:37], v[94:97], v[102:105], v[34:37]
	v_mfma_f32_16x16x32_bf16 v[30:33], v[98:101], v[102:105], v[30:33]
	v_mfma_f32_16x16x32_bf16 v[26:29], v[94:97], v[106:109], v[26:29]
	v_mfma_f32_16x16x32_bf16 v[22:25], v[98:101], v[106:109], v[22:25]
	ds_read_b128 v[102:105], v84 offset:4096
	ds_read_b128 v[106:109], v84 offset:6144
	s_waitcnt lgkmcnt(0)
	v_mfma_f32_16x16x32_bf16 v[18:21], v[94:97], v[102:105], v[18:21]
	v_mfma_f32_16x16x32_bf16 v[14:17], v[98:101], v[102:105], v[14:17]
	v_mfma_f32_16x16x32_bf16 v[10:13], v[94:97], v[106:109], v[10:13]
	v_mfma_f32_16x16x32_bf16 v[6:9], v[98:101], v[106:109], v[4:7]
	s_or_b64 exec, exec, s[6:7]
	v_readfirstlane_b32 s6, v56
	s_add_i32 m0, s6, 0x1a000
	v_lshl_add_u64 v[110:111], v[46:47], 0, s[56:57]
	global_load_lds_dwordx4 v[110:111], off
	v_or_b32_e32 v2, 0x2c0, v38
	s_add_i32 m0, s6, 0x22000
	v_lshl_add_u64 v[110:111], v[2:3], 1, s[18:19]
	global_load_lds_dwordx4 v[110:111], off
	s_add_i32 m0, s6, 0x1c000
	v_lshl_add_u64 v[110:111], v[48:49], 0, s[56:57]
	global_load_lds_dwordx4 v[110:111], off
	s_add_i32 m0, s6, 0x1e000
	v_lshl_add_u64 v[110:111], v[50:51], 0, s[56:57]
	global_load_lds_dwordx4 v[110:111], off
	s_add_i32 m0, s6, 0x20000
	v_lshl_add_u64 v[110:111], v[52:53], 0, s[56:57]
	global_load_lds_dwordx4 v[110:111], off
	s_branch .LBB0_1545
.Lthin_nc_9:
	s_or_b64 exec, exec, s[6:7]
	v_readfirstlane_b32 s6, v56
	s_add_i32 m0, s6, 0x1a000
	v_lshl_add_u64 v[110:111], v[46:47], 0, s[56:57]
	global_load_lds_dwordx4 v[110:111], off
	v_or_b32_e32 v2, 0x2c0, v38
	s_add_i32 m0, s6, 0x22000
	v_lshl_add_u64 v[110:111], v[2:3], 1, s[18:19]
	global_load_lds_dwordx4 v[110:111], off
	s_add_i32 m0, s6, 0x1c000
	v_lshl_add_u64 v[110:111], v[48:49], 0, s[56:57]
	global_load_lds_dwordx4 v[110:111], off
	s_add_i32 m0, s6, 0x1e000
	v_lshl_add_u64 v[110:111], v[50:51], 0, s[56:57]
	global_load_lds_dwordx4 v[110:111], off
	s_add_i32 m0, s6, 0x20000
	v_lshl_add_u64 v[110:111], v[52:53], 0, s[56:57]
	global_load_lds_dwordx4 v[110:111], off
.LBB0_1545:
	s_or_b64 exec, exec, s[6:7]
	s_waitcnt vmcnt(5)
	s_barrier
	s_and_saveexec_b64 s[6:7], s[4:5]
	s_cbranch_execz .Lthin_nc_10
	ds_read_b128 v[94:97], v87
	ds_read_b128 v[98:101], v87 offset:2048
	ds_read_b128 v[102:105], v86
	ds_read_b128 v[106:109], v86 offset:2048
	s_waitcnt lgkmcnt(0)
	v_mfma_f32_16x16x32_bf16 v[34:37], v[94:97], v[102:105], v[34:37]
	v_mfma_f32_16x16x32_bf16 v[30:33], v[98:101], v[102:105], v[30:33]
	v_mfma_f32_16x16x32_bf16 v[26:29], v[94:97], v[106:109], v[26:29]
	v_mfma_f32_16x16x32_bf16 v[22:25], v[98:101], v[106:109], v[22:25]
	ds_read_b128 v[102:105], v86 offset:4096
	ds_read_b128 v[106:109], v86 offset:6144
	s_waitcnt lgkmcnt(0)
	v_mfma_f32_16x16x32_bf16 v[18:21], v[94:97], v[102:105], v[18:21]
	v_mfma_f32_16x16x32_bf16 v[10:13], v[94:97], v[106:109], v[10:13]
	ds_read_b128 v[94:97], v89
	v_mfma_f32_16x16x32_bf16 v[14:17], v[98:101], v[102:105], v[14:17]
	v_mfma_f32_16x16x32_bf16 v[4:7], v[98:101], v[106:109], v[6:9]
	ds_read_b128 v[98:101], v89 offset:2048
	ds_read_b128 v[102:105], v88
	ds_read_b128 v[106:109], v88 offset:2048
	s_waitcnt lgkmcnt(0)
	v_mfma_f32_16x16x32_bf16 v[34:37], v[94:97], v[102:105], v[34:37]
	v_mfma_f32_16x16x32_bf16 v[30:33], v[98:101], v[102:105], v[30:33]
	v_mfma_f32_16x16x32_bf16 v[26:29], v[94:97], v[106:109], v[26:29]
	v_mfma_f32_16x16x32_bf16 v[22:25], v[98:101], v[106:109], v[22:25]
	ds_read_b128 v[102:105], v88 offset:4096
	ds_read_b128 v[106:109], v88 offset:6144
	s_waitcnt lgkmcnt(0)
	v_mfma_f32_16x16x32_bf16 v[18:21], v[94:97], v[102:105], v[18:21]
	v_mfma_f32_16x16x32_bf16 v[14:17], v[98:101], v[102:105], v[14:17]
	v_mfma_f32_16x16x32_bf16 v[10:13], v[94:97], v[106:109], v[10:13]
	v_mfma_f32_16x16x32_bf16 v[6:9], v[98:101], v[106:109], v[4:7]
	s_or_b64 exec, exec, s[6:7]
	v_readfirstlane_b32 s6, v56
	s_add_i32 m0, s6, 0x0
	v_lshl_add_u64 v[110:111], v[46:47], 0, s[58:59]
	global_load_lds_dwordx4 v[110:111], off
	v_or_b32_e32 v2, 0x300, v38
	s_add_i32 m0, s6, 0x8000
	v_lshl_add_u64 v[110:111], v[2:3], 1, s[18:19]
	global_load_lds_dwordx4 v[110:111], off
	s_add_i32 m0, s6, 0x2000
	v_lshl_add_u64 v[110:111], v[48:49], 0, s[58:59]
	global_load_lds_dwordx4 v[110:111], off
	s_add_i32 m0, s6, 0x4000
	v_lshl_add_u64 v[110:111], v[50:51], 0, s[58:59]
	global_load_lds_dwordx4 v[110:111], off
	s_add_i32 m0, s6, 0x6000
	v_lshl_add_u64 v[110:111], v[52:53], 0, s[58:59]
	global_load_lds_dwordx4 v[110:111], off
	s_branch .LBB0_1547
; #define GLDS16(gp, lp) __builtin_amdgcn_global_load_lds((const unsigned*)(gp), (__attribute__((address_space(3))) unsigned*)(lp), 16, 0, 0)
; template <bool SWAP, class Epi, bool THIN = false> ...
;     ...
;     for (int st = 0; st < ns; ++st) {
;       asm volatile("s_waitcnt vmcnt(0)" ::: "memory");
;       __builtin_amdgcn_s_barrier();
;       asm volatile("" ::: "memory");
;       if (st + 1 < ns) {
;         char* nb = smem + ((st + 1) & 1) * 65536;
;         const int ko = (st + 1) * 64;
; #pragma unroll
;         for (int i = 0; i < 4; ++i) { GLDS16(A + (size_t)(ap[i] + ko), nb + tid * 16 + i * 8192); GLDS16(Bt + (size_t)(bp[i] + ko), nb + 32768 + tid * 16 + i * 8192); }
;       }
;       const char* sa = smem + (st & 1) * 65536 + (wr * 64 + fr) * 128;
;       const char* sb = smem + (st & 1) * 65536 + 32768 + (wc * 128 + fr) * 128;
;       if constexpr (THIN) {
;         if (wc == 0) {
; #pragma unroll
;           for (int ks = 0; ks < 2; ++ks) {
;             bf16x8 af[4], bf[2];
; #pragma unroll
;             for (int m = 0; m < 4; ++m) af[m] = *(const bf16x8*)(sa + m * 2048 + (((ks * 4 + fq) ^ swz) << 4));
; #pragma unroll
;             for (int n = 0; n < 2; ++n) bf[n] = *(const bf16x8*)(sb + n * 2048 + (((ks * 4 + fq) ^ swz) << 4));
; #pragma unroll
;             for (int m = 0; m < 4; ++m)
; #pragma unroll
;               for (int n = 0; n < 2; ++n)
;                 acc[m][n] = SWAP ? __builtin_amdgcn_mfma_f32_16x16x32_bf16(bf[n], af[m], acc[m][n], 0, 0, 0)
;                                  : __builtin_amdgcn_mfma_f32_16x16x32_bf16(af[m], bf[n], acc[m][n], 0, 0, 0);
;           }
;         }
.Lthin_nc_10:
	s_or_b64 exec, exec, s[6:7]
	v_readfirstlane_b32 s6, v56
	s_add_i32 m0, s6, 0x0
	v_lshl_add_u64 v[110:111], v[46:47], 0, s[58:59]
	global_load_lds_dwordx4 v[110:111], off
	v_or_b32_e32 v2, 0x300, v38
	s_add_i32 m0, s6, 0x8000
	v_lshl_add_u64 v[110:111], v[2:3], 1, s[18:19]
	global_load_lds_dwordx4 v[110:111], off
	s_add_i32 m0, s6, 0x2000
	v_lshl_add_u64 v[110:111], v[48:49], 0, s[58:59]
	global_load_lds_dwordx4 v[110:111], off
	s_add_i32 m0, s6, 0x4000
	v_lshl_add_u64 v[110:111], v[50:51], 0, s[58:59]
	global_load_lds_dwordx4 v[110:111], off
	s_add_i32 m0, s6, 0x6000
	v_lshl_add_u64 v[110:111], v[52:53], 0, s[58:59]
	global_load_lds_dwordx4 v[110:111], off
.LBB0_1547:
	s_or_b64 exec, exec, s[6:7]
	s_waitcnt vmcnt(5)
	s_barrier
	s_and_saveexec_b64 s[6:7], s[4:5]
	s_cbranch_execz .Lthin_nc_11
	ds_read_b128 v[94:97], v119 offset:32768
	ds_read_b128 v[98:101], v119 offset:34816
	ds_read_b128 v[102:105], v118
	ds_read_b128 v[106:109], v118 offset:2048
	s_waitcnt lgkmcnt(0)
	v_mfma_f32_16x16x32_bf16 v[34:37], v[94:97], v[102:105], v[34:37]
	v_mfma_f32_16x16x32_bf16 v[30:33], v[98:101], v[102:105], v[30:33]
	v_mfma_f32_16x16x32_bf16 v[26:29], v[94:97], v[106:109], v[26:29]
	v_mfma_f32_16x16x32_bf16 v[22:25], v[98:101], v[106:109], v[22:25]
	ds_read_b128 v[102:105], v118 offset:4096
	ds_read_b128 v[106:109], v118 offset:6144
	s_waitcnt lgkmcnt(0)
	v_mfma_f32_16x16x32_bf16 v[18:21], v[94:97], v[102:105], v[18:21]
	v_mfma_f32_16x16x32_bf16 v[10:13], v[94:97], v[106:109], v[10:13]
	ds_read_b128 v[94:97], v121 offset:32768
	v_mfma_f32_16x16x32_bf16 v[14:17], v[98:101], v[102:105], v[14:17]
	v_mfma_f32_16x16x32_bf16 v[4:7], v[98:101], v[106:109], v[6:9]
	ds_read_b128 v[98:101], v121 offset:34816
	ds_read_b128 v[102:105], v120
	ds_read_b128 v[106:109], v120 offset:2048
	s_waitcnt lgkmcnt(0)
	v_mfma_f32_16x16x32_bf16 v[34:37], v[94:97], v[102:105], v[34:37]
	v_mfma_f32_16x16x32_bf16 v[30:33], v[98:101], v[102:105], v[30:33]
	v_mfma_f32_16x16x32_bf16 v[26:29], v[94:97], v[106:109], v[26:29]
	v_mfma_f32_16x16x32_bf16 v[22:25], v[98:101], v[106:109], v[22:25]
	ds_read_b128 v[102:105], v120 offset:4096
	ds_read_b128 v[106:109], v120 offset:6144
	s_waitcnt lgkmcnt(0)
	v_mfma_f32_16x16x32_bf16 v[18:21], v[94:97], v[102:105], v[18:21]
	v_mfma_f32_16x16x32_bf16 v[14:17], v[98:101], v[102:105], v[14:17]
	v_mfma_f32_16x16x32_bf16 v[10:13], v[94:97], v[106:109], v[10:13]
	v_mfma_f32_16x16x32_bf16 v[6:9], v[98:101], v[106:109], v[4:7]
	s_or_b64 exec, exec, s[6:7]
	v_readfirstlane_b32 s6, v56
	s_add_i32 m0, s6, 0x10000
	v_lshl_add_u64 v[110:111], v[46:47], 0, s[60:61]
	global_load_lds_dwordx4 v[110:111], off
	v_or_b32_e32 v2, 0x340, v38
	s_add_i32 m0, s6, 0x18000
	v_lshl_add_u64 v[110:111], v[2:3], 1, s[18:19]
	global_load_lds_dwordx4 v[110:111], off
	s_add_i32 m0, s6, 0x12000
	v_lshl_add_u64 v[110:111], v[48:49], 0, s[60:61]
	global_load_lds_dwordx4 v[110:111], off
	s_add_i32 m0, s6, 0x14000
	v_lshl_add_u64 v[110:111], v[50:51], 0, s[60:61]
	global_load_lds_dwordx4 v[110:111], off
	s_add_i32 m0, s6, 0x16000
	v_lshl_add_u64 v[110:111], v[52:53], 0, s[60:61]
	global_load_lds_dwordx4 v[110:111], off
	s_branch .LBB0_1549
.Lthin_nc_11:
	s_or_b64 exec, exec, s[6:7]
	v_readfirstlane_b32 s6, v56
	s_add_i32 m0, s6, 0x10000
	v_lshl_add_u64 v[110:111], v[46:47], 0, s[60:61]
	global_load_lds_dwordx4 v[110:111], off
	v_or_b32_e32 v2, 0x340, v38
	s_add_i32 m0, s6, 0x18000
	v_lshl_add_u64 v[110:111], v[2:3], 1, s[18:19]
	global_load_lds_dwordx4 v[110:111], off
	s_add_i32 m0, s6, 0x12000
	v_lshl_add_u64 v[110:111], v[48:49], 0, s[60:61]
	global_load_lds_dwordx4 v[110:111], off
	s_add_i32 m0, s6, 0x14000
	v_lshl_add_u64 v[110:111], v[50:51], 0, s[60:61]
	global_load_lds_dwordx4 v[110:111], off
	s_add_i32 m0, s6, 0x16000
	v_lshl_add_u64 v[110:111], v[52:53], 0, s[60:61]
	global_load_lds_dwordx4 v[110:111], off
; #define GLDS16(gp, lp) __builtin_amdgcn_global_load_lds((const unsigned*)(gp), (__attribute__((address_space(3))) unsigned*)(lp), 16, 0, 0)
; template <bool SWAP, class Epi, bool THIN = false> ...
;     ...
;     for (int st = 0; st < ns; ++st) {
;       asm volatile("s_waitcnt vmcnt(0)" ::: "memory");
;       __builtin_amdgcn_s_barrier();
;       asm volatile("" ::: "memory");
;       if (st + 1 < ns) {
;         char* nb = smem + ((st + 1) & 1) * 65536;
;         const int ko = (st + 1) * 64;
; #pragma unroll
;         for (int i = 0; i < 4; ++i) { GLDS16(A + (size_t)(ap[i] + ko), nb + tid * 16 + i * 8192); GLDS16(Bt + (size_t)(bp[i] + ko), nb + 32768 + tid * 16 + i * 8192); }
;       }
;       const char* sa = smem + (st & 1) * 65536 + (wr * 64 + fr) * 128;
;       const char* sb = smem + (st & 1) * 65536 + 32768 + (wc * 128 + fr) * 128;
;       if constexpr (THIN) {
;         if (wc == 0) {
; #pragma unroll
;           for (int ks = 0; ks < 2; ++ks) {
;             bf16x8 af[4], bf[2];
; #pragma unroll
;             for (int m = 0; m < 4; ++m) af[m] = *(const bf16x8*)(sa + m * 2048 + (((ks * 4 + fq) ^ swz) << 4));
; #pragma unroll
;             for (int n = 0; n < 2; ++n) bf[n] = *(const bf16x8*)(sb + n * 2048 + (((ks * 4 + fq) ^ swz) << 4));
; #pragma unroll
;             for (int m = 0; m < 4; ++m)
; #pragma unroll
;               for (int n = 0; n < 2; ++n)
;                 acc[m][n] = SWAP ? __builtin_amdgcn_mfma_f32_16x16x32_bf16(bf[n], af[m], acc[m][n], 0, 0, 0)
;                                  : __builtin_amdgcn_mfma_f32_16x16x32_bf16(af[m], bf[n], acc[m][n], 0, 0, 0);
;           }
;         }
.LBB0_1549:
	s_or_b64 exec, exec, s[6:7]
	s_waitcnt vmcnt(5)
	s_barrier
	s_and_saveexec_b64 s[6:7], s[4:5]
	s_cbranch_execz .Lthin_nc_12
	ds_read_b128 v[94:97], v83 offset:32768
	ds_read_b128 v[98:101], v83 offset:34816
	ds_read_b128 v[102:105], v82
	ds_read_b128 v[106:109], v82 offset:2048
	s_waitcnt lgkmcnt(0)
	v_mfma_f32_16x16x32_bf16 v[34:37], v[94:97], v[102:105], v[34:37]
	v_mfma_f32_16x16x32_bf16 v[30:33], v[98:101], v[102:105], v[30:33]
	v_mfma_f32_16x16x32_bf16 v[26:29], v[94:97], v[106:109], v[26:29]
	v_mfma_f32_16x16x32_bf16 v[22:25], v[98:101], v[106:109], v[22:25]
	ds_read_b128 v[102:105], v82 offset:4096
	ds_read_b128 v[106:109], v82 offset:6144
	s_waitcnt lgkmcnt(0)
	v_mfma_f32_16x16x32_bf16 v[18:21], v[94:97], v[102:105], v[18:21]
	v_mfma_f32_16x16x32_bf16 v[10:13], v[94:97], v[106:109], v[10:13]
	ds_read_b128 v[94:97], v85 offset:32768
	v_mfma_f32_16x16x32_bf16 v[14:17], v[98:101], v[102:105], v[14:17]
	v_mfma_f32_16x16x32_bf16 v[4:7], v[98:101], v[106:109], v[6:9]
	ds_read_b128 v[98:101], v85 offset:34816
	ds_read_b128 v[102:105], v84
	ds_read_b128 v[106:109], v84 offset:2048
	s_waitcnt lgkmcnt(0)
	v_mfma_f32_16x16x32_bf16 v[34:37], v[94:97], v[102:105], v[34:37]
	v_mfma_f32_16x16x32_bf16 v[30:33], v[98:101], v[102:105], v[30:33]
	v_mfma_f32_16x16x32_bf16 v[26:29], v[94:97], v[106:109], v[26:29]
	v_mfma_f32_16x16x32_bf16 v[22:25], v[98:101], v[106:109], v[22:25]
	ds_read_b128 v[102:105], v84 offset:4096
	ds_read_b128 v[106:109], v84 offset:6144
	s_waitcnt lgkmcnt(0)
	v_mfma_f32_16x16x32_bf16 v[18:21], v[94:97], v[102:105], v[18:21]
	v_mfma_f32_16x16x32_bf16 v[14:17], v[98:101], v[102:105], v[14:17]
	v_mfma_f32_16x16x32_bf16 v[10:13], v[94:97], v[106:109], v[10:13]
	v_mfma_f32_16x16x32_bf16 v[6:9], v[98:101], v[106:109], v[4:7]
	s_or_b64 exec, exec, s[6:7]
	v_readfirstlane_b32 s6, v56
	s_add_i32 m0, s6, 0x1a000
	v_lshl_add_u64 v[110:111], v[46:47], 0, s[62:63]
	global_load_lds_dwordx4 v[110:111], off
	v_or_b32_e32 v2, 0x380, v38
	s_add_i32 m0, s6, 0x22000
	v_lshl_add_u64 v[110:111], v[2:3], 1, s[18:19]
	global_load_lds_dwordx4 v[110:111], off
	s_add_i32 m0, s6, 0x1c000
	v_lshl_add_u64 v[110:111], v[48:49], 0, s[62:63]
	global_load_lds_dwordx4 v[110:111], off
	s_add_i32 m0, s6, 0x1e000
	v_lshl_add_u64 v[110:111], v[50:51], 0, s[62:63]
	global_load_lds_dwordx4 v[110:111], off
	s_add_i32 m0, s6, 0x20000
	v_lshl_add_u64 v[110:111], v[52:53], 0, s[62:63]
	global_load_lds_dwordx4 v[110:111], off
	s_branch .LBB0_1551
.Lthin_nc_12:
	s_or_b64 exec, exec, s[6:7]
	v_readfirstlane_b32 s6, v56
	s_add_i32 m0, s6, 0x1a000
	v_lshl_add_u64 v[110:111], v[46:47], 0, s[62:63]
	global_load_lds_dwordx4 v[110:111], off
	v_or_b32_e32 v2, 0x380, v38
	s_add_i32 m0, s6, 0x22000
	v_lshl_add_u64 v[110:111], v[2:3], 1, s[18:19]
	global_load_lds_dwordx4 v[110:111], off
	s_add_i32 m0, s6, 0x1c000
	v_lshl_add_u64 v[110:111], v[48:49], 0, s[62:63]
	global_load_lds_dwordx4 v[110:111], off
	s_add_i32 m0, s6, 0x1e000
	v_lshl_add_u64 v[110:111], v[50:51], 0, s[62:63]
	global_load_lds_dwordx4 v[110:111], off
	s_add_i32 m0, s6, 0x20000
	v_lshl_add_u64 v[110:111], v[52:53], 0, s[62:63]
	global_load_lds_dwordx4 v[110:111], off
.LBB0_1551:
	s_or_b64 exec, exec, s[6:7]
	s_waitcnt vmcnt(5)
	s_barrier
	s_and_saveexec_b64 s[6:7], s[4:5]
	s_cbranch_execz .Lthin_nc_13
	ds_read_b128 v[94:97], v87
	ds_read_b128 v[98:101], v87 offset:2048
	ds_read_b128 v[102:105], v86
	ds_read_b128 v[106:109], v86 offset:2048
	s_waitcnt lgkmcnt(0)
	v_mfma_f32_16x16x32_bf16 v[34:37], v[94:97], v[102:105], v[34:37]
	v_mfma_f32_16x16x32_bf16 v[30:33], v[98:101], v[102:105], v[30:33]
	v_mfma_f32_16x16x32_bf16 v[26:29], v[94:97], v[106:109], v[26:29]
	v_mfma_f32_16x16x32_bf16 v[22:25], v[98:101], v[106:109], v[22:25]
	ds_read_b128 v[102:105], v86 offset:4096
	ds_read_b128 v[106:109], v86 offset:6144
	s_waitcnt lgkmcnt(0)
	v_mfma_f32_16x16x32_bf16 v[18:21], v[94:97], v[102:105], v[18:21]
	v_mfma_f32_16x16x32_bf16 v[10:13], v[94:97], v[106:109], v[10:13]
	ds_read_b128 v[94:97], v89
	v_mfma_f32_16x16x32_bf16 v[14:17], v[98:101], v[102:105], v[14:17]
	v_mfma_f32_16x16x32_bf16 v[4:7], v[98:101], v[106:109], v[6:9]
	ds_read_b128 v[98:101], v89 offset:2048
	ds_read_b128 v[102:105], v88
	ds_read_b128 v[106:109], v88 offset:2048
	s_waitcnt lgkmcnt(0)
	v_mfma_f32_16x16x32_bf16 v[34:37], v[94:97], v[102:105], v[34:37]
	v_mfma_f32_16x16x32_bf16 v[30:33], v[98:101], v[102:105], v[30:33]
	v_mfma_f32_16x16x32_bf16 v[26:29], v[94:97], v[106:109], v[26:29]
	v_mfma_f32_16x16x32_bf16 v[22:25], v[98:101], v[106:109], v[22:25]
	ds_read_b128 v[102:105], v88 offset:4096
	ds_read_b128 v[106:109], v88 offset:6144
	s_waitcnt lgkmcnt(0)
	v_mfma_f32_16x16x32_bf16 v[18:21], v[94:97], v[102:105], v[18:21]
	v_mfma_f32_16x16x32_bf16 v[14:17], v[98:101], v[102:105], v[14:17]
	v_mfma_f32_16x16x32_bf16 v[10:13], v[94:97], v[106:109], v[10:13]
	v_mfma_f32_16x16x32_bf16 v[6:9], v[98:101], v[106:109], v[4:7]
	s_or_b64 exec, exec, s[6:7]
	v_readfirstlane_b32 s6, v56
	s_add_i32 m0, s6, 0x0
	v_lshl_add_u64 v[110:111], v[46:47], 0, s[64:65]
	global_load_lds_dwordx4 v[110:111], off
	v_or_b32_e32 v2, 0x3c0, v38
	s_add_i32 m0, s6, 0x8000
	v_lshl_add_u64 v[110:111], v[2:3], 1, s[18:19]
	global_load_lds_dwordx4 v[110:111], off
	s_add_i32 m0, s6, 0x2000
	v_lshl_add_u64 v[110:111], v[48:49], 0, s[64:65]
	global_load_lds_dwordx4 v[110:111], off
	s_add_i32 m0, s6, 0x4000
	v_lshl_add_u64 v[110:111], v[50:51], 0, s[64:65]
	global_load_lds_dwordx4 v[110:111], off
	s_add_i32 m0, s6, 0x6000
	v_lshl_add_u64 v[110:111], v[52:53], 0, s[64:65]
	global_load_lds_dwordx4 v[110:111], off
	s_branch .LBB0_1553
.Lthin_nc_13:
	s_or_b64 exec, exec, s[6:7]
	v_readfirstlane_b32 s6, v56
	s_add_i32 m0, s6, 0x0
	v_lshl_add_u64 v[110:111], v[46:47], 0, s[64:65]
	global_load_lds_dwordx4 v[110:111], off
	v_or_b32_e32 v2, 0x3c0, v38
	s_add_i32 m0, s6, 0x8000
	v_lshl_add_u64 v[110:111], v[2:3], 1, s[18:19]
	global_load_lds_dwordx4 v[110:111], off
	s_add_i32 m0, s6, 0x2000
	v_lshl_add_u64 v[110:111], v[48:49], 0, s[64:65]
	global_load_lds_dwordx4 v[110:111], off
	s_add_i32 m0, s6, 0x4000
	v_lshl_add_u64 v[110:111], v[50:51], 0, s[64:65]
	global_load_lds_dwordx4 v[110:111], off
	s_add_i32 m0, s6, 0x6000
	v_lshl_add_u64 v[110:111], v[52:53], 0, s[64:65]
	global_load_lds_dwordx4 v[110:111], off
